# attention: tiles at band distance >= 3 chunks skip the (constant) bias tile reads; constant folded into row max and exp2 offset
# speedup vs baseline: 1.0271x; 1.0093x over previous
; #define LAS __attribute__((address_space(3)))
; __device__ __forceinline__ void attn_tile(const LAS unsigned char* Kb, const LAS unsigned char* Vb, const LAS f32x4* bp, const bf16x8 (&qr)[4], f32x16 (&o)[2], float& m, float& l, int r32, int hi) {
;     const float C2 = 0.125f * LOG2E;
;     f32x16 p0, p1;
; #pragma unroll
;     for (int j = 0; j < 4; ++j) { const f32x4 t0 = bp[j * 64], t1 = bp[(4 + j) * 64];
;         p0[4 * j] = t0[0]; p0[4 * j + 1] = t0[1]; p0[4 * j + 2] = t0[2]; p0[4 * j + 3] = t0[3]; p1[4 * j] = t1[0]; p1[4 * j + 1] = t1[1]; p1[4 * j + 2] = t1[2]; p1[4 * j + 3] = t1[3]; }
; #pragma unroll
;     for (int d0 = 0; d0 < 4; ++d0) {
;         const bf16x8 a0 = *(const LAS bf16x8*)(Kb + r32 * 144 + d0 * 32 + hi * 16);
;         const bf16x8 a1 = *(const LAS bf16x8*)(Kb + (32 + r32) * 144 + d0 * 32 + hi * 16);
;         p0 = __builtin_amdgcn_mfma_f32_32x32x16_bf16(a0, qr[d0], p0, 0, 0, 0);
;         p1 = __builtin_amdgcn_mfma_f32_32x32x16_bf16(a1, qr[d0], p1, 0, 0, 0);
;     }
;     float mx = fmaxf(p0[0], p1[0]);
; #pragma unroll
;     for (int r = 1; r < 16; ++r) mx = fmaxf(mx, fmaxf(p0[r], p1[r]));
;     mx = fmaxf(mx, __shfl_xor(mx, 32)) * C2;
;     if (__any(mx > m + 8.0f)) {
;         const float mn = fmaxf(m, mx), scl = __builtin_amdgcn_exp2f(m - mn); m = mn; l *= scl;
; #pragma unroll
;         for (int r = 0; r < 16; ++r) { o[0][r] *= scl; o[1][r] *= scl; }
;     }
;     float ls = 0.f; const float nm = -m;
; #pragma unroll
;     for (int r = 0; r < 16; ++r) { p0[r] = __builtin_amdgcn_exp2f(p0[r] * C2 + nm); p1[r] = __builtin_amdgcn_exp2f(p1[r] * C2 + nm); ls += p0[r] + p1[r]; }
; __device__ __forceinline__ void attn_prompt_unit(const Params& P, LAS unsigned char* lds, int li, int b, int h, int g4, const int tid) {
;     ...
;         if (kt >= cw - 8 && kt <= cw) attn_tile(lds + AT_KOFF, lds + AT_VOFF, btl + min(cw - kt, 3) * 1024, qr, o, m, l, r32, hi);
.LBB0_73:
	s_cmp_lt_i32 s28, s25
	s_cselect_b64 s[30:31], -1, 0
	s_cmp_gt_i32 s28, s23
	s_cselect_b64 s[34:35], -1, 0
	s_or_b64 s[30:31], s[30:31], s[34:35]
	s_and_b64 vcc, exec, s[30:31]
	s_cbranch_vccnz .LBB0_77
	s_add_i32 s29, s22, s26
	s_add_i32 s29, s29, 1
	s_min_i32 s29, s29, 3
	s_cmp_eq_u32 s29, 3
	s_cbranch_scc1 .Latt_const_a
	v_lshl_add_u32 v158, s29, 14, v103
	ds_read_b128 v[48:51], v158 offset:36864
	ds_read_b128 v[52:55], v158 offset:37888
	ds_read_b128 v[56:59], v158 offset:38912
	ds_read_b128 v[60:63], v158 offset:39936
	ds_read_b128 v[138:141], v116 offset:0
	ds_read_b128 v[142:145], v116 offset:4608
	ds_read_b128 v[32:35], v158 offset:40960
	ds_read_b128 v[36:39], v158 offset:41984
	ds_read_b128 v[40:43], v158 offset:43008
	ds_read_b128 v[44:47], v158 offset:44032
	ds_read_b128 v[146:149], v116 offset:32
	ds_read_b128 v[150:153], v116 offset:4640
	ds_read_b128 v[154:157], v116 offset:64
	ds_read_b128 v[118:121], v116 offset:4672
	ds_read_b128 v[122:125], v116 offset:96
	v_add_u32_e32 v133, v113, v112
	v_xor_b32_e32 v132, 32, v200
	s_waitcnt vmcnt(2) lgkmcnt(10)
	v_mfma_f32_32x32x16_bf16 v[48:63], v[138:141], v[64:67], v[48:63]
	ds_read_b128 v[126:129], v116 offset:4704
	s_waitcnt lgkmcnt(6)
	v_mfma_f32_32x32x16_bf16 v[32:47], v[142:145], v[64:67], v[32:47]
	v_lshlrev_b32_e32 v132, 2, v132
	s_waitcnt lgkmcnt(5)
	v_mfma_f32_32x32x16_bf16 v[48:63], v[146:149], v[68:71], v[48:63]
	s_waitcnt lgkmcnt(4)
	v_mfma_f32_32x32x16_bf16 v[32:47], v[150:153], v[68:71], v[32:47]
	s_waitcnt lgkmcnt(3)
	v_mfma_f32_32x32x16_bf16 v[48:63], v[154:157], v[72:75], v[48:63]
	s_waitcnt lgkmcnt(2)
	v_mfma_f32_32x32x16_bf16 v[32:47], v[118:121], v[72:75], v[32:47]
	s_waitcnt lgkmcnt(1)
	v_mfma_f32_32x32x16_bf16 v[48:63], v[122:125], v[80:83], v[48:63]
	s_waitcnt lgkmcnt(0)
	v_mfma_f32_32x32x16_bf16 v[32:47], v[126:129], v[80:83], v[32:47]
	ds_read_b128 v[138:141], v133 offset:18432
	ds_read_b128 v[142:145], v133 offset:18464
	ds_read_b128 v[146:149], v133 offset:18496
	ds_read_b128 v[150:153], v133 offset:18528
	ds_read_b128 v[154:157], v133 offset:23040
	ds_read_b128 v[118:121], v133 offset:23072
	ds_read_b128 v[122:125], v133 offset:23104
	ds_read_b128 v[126:129], v133 offset:23136
	v_add_f32_e32 v159, 0x41000000, v117
	s_nop 1
	v_max3_f32 v130, v48, v49, v50
	v_max3_f32 v130, v130, v51, v52
	v_max3_f32 v130, v130, v53, v54
	v_max3_f32 v131, v32, v33, v34
	v_max3_f32 v130, v130, v55, v56
	v_max3_f32 v131, v131, v35, v36
	v_max3_f32 v130, v130, v57, v58
	v_max3_f32 v131, v131, v37, v38
	v_max3_f32 v130, v130, v59, v60
	v_max3_f32 v131, v131, v39, v40
	v_max3_f32 v130, v130, v61, v62
	v_max3_f32 v131, v131, v41, v42
	v_max_f32_e32 v130, v130, v63
	v_max3_f32 v131, v131, v43, v44
	v_max3_f32 v131, v131, v45, v46
	v_max_f32_e32 v131, v131, v47
	v_max_f32_e32 v130, v130, v131
	ds_bpermute_b32 v131, v132, v130
	s_waitcnt lgkmcnt(0)
	v_max_f32_e32 v130, v130, v131
	v_mul_f32_e32 v130, 0x3e38aa3b, v130
	v_cmp_gt_f32_e32 vcc, v130, v159
	s_cbranch_vccz .Latt_keep_a
	v_max_f32_e32 v131, v117, v130
	v_sub_f32_e32 v117, v117, v131
	v_exp_f32_e32 v130, v117
	v_mov_b32_e32 v117, v131
	v_mul_f32_e32 v101, v101, v130
	v_pk_mul_f32 v[0:1], v[0:1], v[130:131] op_sel_hi:[1,0]
	v_pk_mul_f32 v[2:3], v[2:3], v[130:131] op_sel_hi:[1,0]
	v_pk_mul_f32 v[4:5], v[4:5], v[130:131] op_sel_hi:[1,0]
	v_pk_mul_f32 v[6:7], v[6:7], v[130:131] op_sel_hi:[1,0]
	v_pk_mul_f32 v[8:9], v[8:9], v[130:131] op_sel_hi:[1,0]
	v_pk_mul_f32 v[10:11], v[10:11], v[130:131] op_sel_hi:[1,0]
	v_pk_mul_f32 v[12:13], v[12:13], v[130:131] op_sel_hi:[1,0]
	v_pk_mul_f32 v[14:15], v[14:15], v[130:131] op_sel_hi:[1,0]
	v_pk_mul_f32 v[16:17], v[16:17], v[130:131] op_sel_hi:[1,0]
	v_pk_mul_f32 v[18:19], v[18:19], v[130:131] op_sel_hi:[1,0]
	v_pk_mul_f32 v[20:21], v[20:21], v[130:131] op_sel_hi:[1,0]
	v_pk_mul_f32 v[22:23], v[22:23], v[130:131] op_sel_hi:[1,0]
	v_pk_mul_f32 v[24:25], v[24:25], v[130:131] op_sel_hi:[1,0]
	v_pk_mul_f32 v[26:27], v[26:27], v[130:131] op_sel_hi:[1,0]
	v_pk_mul_f32 v[28:29], v[28:29], v[130:131] op_sel_hi:[1,0]
	v_pk_mul_f32 v[30:31], v[30:31], v[130:131] op_sel_hi:[1,0]
.Latt_keep_a:
	v_fma_f32 v48, v48, s6, -v117
	v_fma_f32 v49, v49, s6, -v117
	v_fma_f32 v50, v50, s6, -v117
	v_fma_f32 v51, v51, s6, -v117
	v_fma_f32 v52, v52, s6, -v117
	v_fma_f32 v53, v53, s6, -v117
	v_fma_f32 v54, v54, s6, -v117
	v_fma_f32 v55, v55, s6, -v117
	v_exp_f32_e32 v48, v48
	v_exp_f32_e32 v49, v49
	v_exp_f32_e32 v50, v50
	v_exp_f32_e32 v51, v51
	v_exp_f32_e32 v52, v52
	v_exp_f32_e32 v53, v53
	v_exp_f32_e32 v54, v54
	v_exp_f32_e32 v55, v55
	v_add_f32_e32 v130, v48, v49
	v_add_f32_e32 v131, v50, v51
	v_add_f32_e32 v130, v130, v52
	v_add_f32_e32 v131, v131, v53
	v_add_f32_e32 v130, v130, v54
	v_add_f32_e32 v131, v131, v55
	v_cvt_pk_bf16_f32 v48, v48, v49
	v_cvt_pk_bf16_f32 v49, v50, v51
	v_cvt_pk_bf16_f32 v50, v52, v53
	v_cvt_pk_bf16_f32 v51, v54, v55
	v_fma_f32 v56, v56, s6, -v117
	v_fma_f32 v57, v57, s6, -v117
	v_fma_f32 v58, v58, s6, -v117
	v_fma_f32 v59, v59, s6, -v117
	v_fma_f32 v60, v60, s6, -v117
	v_fma_f32 v61, v61, s6, -v117
	v_fma_f32 v62, v62, s6, -v117
	v_fma_f32 v63, v63, s6, -v117
	v_exp_f32_e32 v56, v56
	v_exp_f32_e32 v57, v57
	v_exp_f32_e32 v58, v58
	v_exp_f32_e32 v59, v59
	v_exp_f32_e32 v60, v60
	v_exp_f32_e32 v61, v61
	v_exp_f32_e32 v62, v62
	v_exp_f32_e32 v63, v63
	v_mfma_f32_32x32x16_bf16 v[16:31], v[138:141], v[48:51], v[16:31]
	v_mfma_f32_32x32x16_bf16 v[0:15], v[154:157], v[48:51], v[0:15]
	v_add_f32_e32 v130, v130, v56
	v_add_f32_e32 v131, v131, v57
	v_add_f32_e32 v130, v130, v58
	v_add_f32_e32 v131, v131, v59
	v_add_f32_e32 v130, v130, v60
	v_add_f32_e32 v131, v131, v61
; #define LAS __attribute__((address_space(3)))
; __device__ __forceinline__ unsigned pk2(float lo, float hi) { const f32x2 v = {lo, hi}; return __builtin_bit_cast(unsigned, __builtin_convertvector(v, hwbf16x2)); }
; __device__ __forceinline__ void attn_tile(const LAS unsigned char* Kb, const LAS unsigned char* Vb, const LAS f32x4* bp, const bf16x8 (&qr)[4], f32x16 (&o)[2], float& m, float& l, int r32, int hi) {
;     ...
;     float ls = 0.f; const float nm = -m;
; #pragma unroll
;     for (int r = 0; r < 16; ++r) { p0[r] = __builtin_amdgcn_exp2f(p0[r] * C2 + nm); p1[r] = __builtin_amdgcn_exp2f(p1[r] * C2 + nm); ls += p0[r] + p1[r]; }
;     l += ls;
;     u32x4 pw[4];
; #pragma unroll
;     for (int s = 0; s < 2; ++s) {
;         pw[s] = (u32x4){pk2(p0[8 * s], p0[8 * s + 1]), pk2(p0[8 * s + 2], p0[8 * s + 3]), pk2(p0[8 * s + 4], p0[8 * s + 5]), pk2(p0[8 * s + 6], p0[8 * s + 7])};
;         pw[2 + s] = (u32x4){pk2(p1[8 * s], p1[8 * s + 1]), pk2(p1[8 * s + 2], p1[8 * s + 3]), pk2(p1[8 * s + 4], p1[8 * s + 5]), pk2(p1[8 * s + 6], p1[8 * s + 7])};
;     }
; #pragma unroll
;     for (int dh = 0; dh < 2; ++dh)
; #pragma unroll
;         for (int ks = 0; ks < 4; ++ks) {
;             const bf16x8 vf = *(const LAS bf16x8*)(Vb + (32 * dh + r32) * 144 + (16 * ks + 8 * hi) * 2);
;             o[dh] = __builtin_amdgcn_mfma_f32_32x32x16_bf16(vf, __builtin_bit_cast(bf16x8, pw[ks]), o[dh], 0, 0, 0);
;         }
	v_add_f32_e32 v130, v130, v62
	v_add_f32_e32 v131, v131, v63
	v_cvt_pk_bf16_f32 v52, v56, v57
	v_cvt_pk_bf16_f32 v53, v58, v59
	v_cvt_pk_bf16_f32 v54, v60, v61
	v_cvt_pk_bf16_f32 v55, v62, v63
	v_fma_f32 v32, v32, s6, -v117
	v_fma_f32 v33, v33, s6, -v117
	v_fma_f32 v34, v34, s6, -v117
	v_fma_f32 v35, v35, s6, -v117
	v_fma_f32 v36, v36, s6, -v117
	v_fma_f32 v37, v37, s6, -v117
	v_fma_f32 v38, v38, s6, -v117
	v_fma_f32 v39, v39, s6, -v117
	v_exp_f32_e32 v32, v32
	v_exp_f32_e32 v33, v33
	v_exp_f32_e32 v34, v34
	v_exp_f32_e32 v35, v35
	v_exp_f32_e32 v36, v36
	v_exp_f32_e32 v37, v37
	v_exp_f32_e32 v38, v38
	v_exp_f32_e32 v39, v39
	v_mfma_f32_32x32x16_bf16 v[16:31], v[142:145], v[52:55], v[16:31]
	v_mfma_f32_32x32x16_bf16 v[0:15], v[118:121], v[52:55], v[0:15]
	v_add_f32_e32 v130, v130, v32
	v_add_f32_e32 v131, v131, v33
	v_add_f32_e32 v130, v130, v34
	v_add_f32_e32 v131, v131, v35
	v_add_f32_e32 v130, v130, v36
	v_add_f32_e32 v131, v131, v37
	v_add_f32_e32 v130, v130, v38
	v_add_f32_e32 v131, v131, v39
	v_cvt_pk_bf16_f32 v32, v32, v33
	v_cvt_pk_bf16_f32 v33, v34, v35
	v_cvt_pk_bf16_f32 v34, v36, v37
	v_cvt_pk_bf16_f32 v35, v38, v39
	v_fma_f32 v40, v40, s6, -v117
	v_fma_f32 v41, v41, s6, -v117
	v_fma_f32 v42, v42, s6, -v117
	v_fma_f32 v43, v43, s6, -v117
	v_fma_f32 v44, v44, s6, -v117
	v_fma_f32 v45, v45, s6, -v117
	v_fma_f32 v46, v46, s6, -v117
	v_fma_f32 v47, v47, s6, -v117
	v_exp_f32_e32 v40, v40
	v_exp_f32_e32 v41, v41
	v_exp_f32_e32 v42, v42
	v_exp_f32_e32 v43, v43
	v_exp_f32_e32 v44, v44
	v_exp_f32_e32 v45, v45
	v_exp_f32_e32 v46, v46
	v_exp_f32_e32 v47, v47
	v_mfma_f32_32x32x16_bf16 v[16:31], v[146:149], v[32:35], v[16:31]
	v_mfma_f32_32x32x16_bf16 v[0:15], v[122:125], v[32:35], v[0:15]
	v_add_f32_e32 v130, v130, v40
	v_add_f32_e32 v131, v131, v41
	v_add_f32_e32 v130, v130, v42
	v_add_f32_e32 v131, v131, v43
	v_add_f32_e32 v130, v130, v44
	v_add_f32_e32 v131, v131, v45
	v_add_f32_e32 v130, v130, v46
	v_add_f32_e32 v131, v131, v47
	v_cvt_pk_bf16_f32 v36, v40, v41
	v_cvt_pk_bf16_f32 v37, v42, v43
	v_cvt_pk_bf16_f32 v38, v44, v45
	v_cvt_pk_bf16_f32 v39, v46, v47
	v_add_f32_e32 v130, v130, v131
	v_add_f32_e32 v101, v101, v130
	v_mfma_f32_32x32x16_bf16 v[16:31], v[150:153], v[36:39], v[16:31]
	v_mfma_f32_32x32x16_bf16 v[0:15], v[126:129], v[36:39], v[0:15]
	s_branch .Latt_done_a
.Latt_const_a:
	v_add_u32_e32 v158, 0xc000, v103
	ds_read_b32 v158, v158 offset:36864
	ds_read_b128 v[138:141], v116 offset:0
	ds_read_b128 v[142:145], v116 offset:4608
	ds_read_b128 v[146:149], v116 offset:32
	ds_read_b128 v[150:153], v116 offset:4640
	ds_read_b128 v[154:157], v116 offset:64
	ds_read_b128 v[118:121], v116 offset:4672
	ds_read_b128 v[122:125], v116 offset:96
	ds_read_b128 v[126:129], v116 offset:4704
	v_add_u32_e32 v133, v113, v112
	v_xor_b32_e32 v132, 32, v200
	s_waitcnt vmcnt(2) lgkmcnt(7)
	v_mfma_f32_32x32x16_bf16 v[48:63], v[138:141], v[64:67], 0
	s_waitcnt lgkmcnt(6)
	v_mfma_f32_32x32x16_bf16 v[32:47], v[142:145], v[64:67], 0
	v_lshlrev_b32_e32 v132, 2, v132
	s_waitcnt lgkmcnt(5)
	v_mfma_f32_32x32x16_bf16 v[48:63], v[146:149], v[68:71], v[48:63]
	s_waitcnt lgkmcnt(4)
	v_mfma_f32_32x32x16_bf16 v[32:47], v[150:153], v[68:71], v[32:47]
	s_waitcnt lgkmcnt(3)
	v_mfma_f32_32x32x16_bf16 v[48:63], v[154:157], v[72:75], v[48:63]
	s_waitcnt lgkmcnt(2)
	v_mfma_f32_32x32x16_bf16 v[32:47], v[118:121], v[72:75], v[32:47]
	s_waitcnt lgkmcnt(1)
	v_mfma_f32_32x32x16_bf16 v[48:63], v[122:125], v[80:83], v[48:63]
	s_waitcnt lgkmcnt(0)
	v_mfma_f32_32x32x16_bf16 v[32:47], v[126:129], v[80:83], v[32:47]
	ds_read_b128 v[138:141], v133 offset:18432
	ds_read_b128 v[142:145], v133 offset:18464
	ds_read_b128 v[146:149], v133 offset:18496
	ds_read_b128 v[150:153], v133 offset:18528
	ds_read_b128 v[154:157], v133 offset:23040
	ds_read_b128 v[118:121], v133 offset:23072
	ds_read_b128 v[122:125], v133 offset:23104
	ds_read_b128 v[126:129], v133 offset:23136
	v_add_f32_e32 v159, 0x41000000, v117
	s_nop 1
	v_max3_f32 v130, v48, v49, v50
	v_max3_f32 v130, v130, v51, v52
	v_max3_f32 v130, v130, v53, v54
	v_max3_f32 v131, v32, v33, v34
	v_max3_f32 v130, v130, v55, v56
	v_max3_f32 v131, v131, v35, v36
	v_max3_f32 v130, v130, v57, v58
	v_max3_f32 v131, v131, v37, v38
	v_max3_f32 v130, v130, v59, v60
	v_max3_f32 v131, v131, v39, v40
	v_max3_f32 v130, v130, v61, v62
	v_max3_f32 v131, v131, v41, v42
	v_max_f32_e32 v130, v130, v63
	v_max3_f32 v131, v131, v43, v44
	v_max3_f32 v131, v131, v45, v46
	v_max_f32_e32 v131, v131, v47
	v_max_f32_e32 v130, v130, v131
	ds_bpermute_b32 v131, v132, v130
	s_waitcnt lgkmcnt(0)
	v_max_f32_e32 v130, v130, v131
	v_add_f32_e32 v130, v130, v158
	v_mul_f32_e32 v130, 0x3e38aa3b, v130
	v_cmp_gt_f32_e32 vcc, v130, v159
	s_cbranch_vccz .Latt_keep_ac
	v_max_f32_e32 v131, v117, v130
	v_sub_f32_e32 v117, v117, v131
	v_exp_f32_e32 v130, v117
	v_mov_b32_e32 v117, v131
	v_mul_f32_e32 v101, v101, v130
	v_pk_mul_f32 v[0:1], v[0:1], v[130:131] op_sel_hi:[1,0]
	v_pk_mul_f32 v[2:3], v[2:3], v[130:131] op_sel_hi:[1,0]
	v_pk_mul_f32 v[4:5], v[4:5], v[130:131] op_sel_hi:[1,0]
	v_pk_mul_f32 v[6:7], v[6:7], v[130:131] op_sel_hi:[1,0]
	v_pk_mul_f32 v[8:9], v[8:9], v[130:131] op_sel_hi:[1,0]
	v_pk_mul_f32 v[10:11], v[10:11], v[130:131] op_sel_hi:[1,0]
	v_pk_mul_f32 v[12:13], v[12:13], v[130:131] op_sel_hi:[1,0]
	v_pk_mul_f32 v[14:15], v[14:15], v[130:131] op_sel_hi:[1,0]
	v_pk_mul_f32 v[16:17], v[16:17], v[130:131] op_sel_hi:[1,0]
	v_pk_mul_f32 v[18:19], v[18:19], v[130:131] op_sel_hi:[1,0]
	v_pk_mul_f32 v[20:21], v[20:21], v[130:131] op_sel_hi:[1,0]
	v_pk_mul_f32 v[22:23], v[22:23], v[130:131] op_sel_hi:[1,0]
	v_pk_mul_f32 v[24:25], v[24:25], v[130:131] op_sel_hi:[1,0]
	v_pk_mul_f32 v[26:27], v[26:27], v[130:131] op_sel_hi:[1,0]
	v_pk_mul_f32 v[28:29], v[28:29], v[130:131] op_sel_hi:[1,0]
	v_pk_mul_f32 v[30:31], v[30:31], v[130:131] op_sel_hi:[1,0]
; #define LAS __attribute__((address_space(3)))
; __device__ __forceinline__ unsigned pk2(float lo, float hi) { const f32x2 v = {lo, hi}; return __builtin_bit_cast(unsigned, __builtin_convertvector(v, hwbf16x2)); }
; #define LDS_BARRIER() asm volatile("s_waitcnt lgkmcnt(0)\n\ts_barrier" ::: "memory")
; #define AT_LOAD(K_, V_, kt) do { const bf16_t* s_ = kvsrc + (size_t)(kt) * 64 * NQKV; K_ = *(const bf16x8*)s_; V_ = *(const bf16x8*)(s_ + 1024); } while (0)
; #define AT_STORE(K_, V_, buf) do { *(LAS bf16x8*)(lds + AT_KOFF + (buf) * 9216 + srow * 144 + sch * 16) = K_; \
;         _Pragma("unroll") for (int j_ = 0; j_ < 8; ++j_) *(LAS short*)(lds + AT_VOFF + (buf) * 9216 + (8 * sch + j_) * 144 + vp * 2) = V_[j_]; } while (0)
; __device__ __forceinline__ void attn_tile(const LAS unsigned char* Kb, const LAS unsigned char* Vb, const LAS f32x4* bp, const bf16x8 (&qr)[4], f32x16 (&o)[2], float& m, float& l, int r32, int hi) {
;     ...
;     float ls = 0.f; const float nm = -m;
; #pragma unroll
;     for (int r = 0; r < 16; ++r) { p0[r] = __builtin_amdgcn_exp2f(p0[r] * C2 + nm); p1[r] = __builtin_amdgcn_exp2f(p1[r] * C2 + nm); ls += p0[r] + p1[r]; }
;     l += ls;
;     u32x4 pw[4];
; #pragma unroll
;     for (int s = 0; s < 2; ++s) {
;         pw[s] = (u32x4){pk2(p0[8 * s], p0[8 * s + 1]), pk2(p0[8 * s + 2], p0[8 * s + 3]), pk2(p0[8 * s + 4], p0[8 * s + 5]), pk2(p0[8 * s + 6], p0[8 * s + 7])};
;         pw[2 + s] = (u32x4){pk2(p1[8 * s], p1[8 * s + 1]), pk2(p1[8 * s + 2], p1[8 * s + 3]), pk2(p1[8 * s + 4], p1[8 * s + 5]), pk2(p1[8 * s + 6], p1[8 * s + 7])};
;     }
; #pragma unroll
;     for (int dh = 0; dh < 2; ++dh)
; #pragma unroll
;         for (int ks = 0; ks < 4; ++ks) {
;             const bf16x8 vf = *(const LAS bf16x8*)(Vb + (32 * dh + r32) * 144 + (16 * ks + 8 * hi) * 2);
;             o[dh] = __builtin_amdgcn_mfma_f32_32x32x16_bf16(vf, __builtin_bit_cast(bf16x8, pw[ks]), o[dh], 0, 0, 0);
;         }
; }
; __device__ __forceinline__ void attn_prompt_unit(const Params& P, LAS unsigned char* lds, int li, int b, int h, int g4, const int tid) {
;     ...
;         AT_STORE(kB, vB, 1);
;         LDS_BARRIER();
;         if (kt + 3 <= kt_hi) AT_LOAD(kB, vB, kt + 3);
.Latt_keep_ac:
	v_fma_f32 v158, -v158, s6, v117
	v_fma_f32 v48, v48, s6, -v158
	v_fma_f32 v49, v49, s6, -v158
	v_fma_f32 v50, v50, s6, -v158
	v_fma_f32 v51, v51, s6, -v158
	v_fma_f32 v52, v52, s6, -v158
	v_fma_f32 v53, v53, s6, -v158
	v_fma_f32 v54, v54, s6, -v158
	v_fma_f32 v55, v55, s6, -v158
	v_exp_f32_e32 v48, v48
	v_exp_f32_e32 v49, v49
	v_exp_f32_e32 v50, v50
	v_exp_f32_e32 v51, v51
	v_exp_f32_e32 v52, v52
	v_exp_f32_e32 v53, v53
	v_exp_f32_e32 v54, v54
	v_exp_f32_e32 v55, v55
	v_add_f32_e32 v130, v48, v49
	v_add_f32_e32 v131, v50, v51
	v_add_f32_e32 v130, v130, v52
	v_add_f32_e32 v131, v131, v53
	v_add_f32_e32 v130, v130, v54
	v_add_f32_e32 v131, v131, v55
	v_cvt_pk_bf16_f32 v48, v48, v49
	v_cvt_pk_bf16_f32 v49, v50, v51
	v_cvt_pk_bf16_f32 v50, v52, v53
	v_cvt_pk_bf16_f32 v51, v54, v55
	v_fma_f32 v56, v56, s6, -v158
	v_fma_f32 v57, v57, s6, -v158
	v_fma_f32 v58, v58, s6, -v158
	v_fma_f32 v59, v59, s6, -v158
	v_fma_f32 v60, v60, s6, -v158
	v_fma_f32 v61, v61, s6, -v158
	v_fma_f32 v62, v62, s6, -v158
	v_fma_f32 v63, v63, s6, -v158
	v_exp_f32_e32 v56, v56
	v_exp_f32_e32 v57, v57
	v_exp_f32_e32 v58, v58
	v_exp_f32_e32 v59, v59
	v_exp_f32_e32 v60, v60
	v_exp_f32_e32 v61, v61
	v_exp_f32_e32 v62, v62
	v_exp_f32_e32 v63, v63
	v_mfma_f32_32x32x16_bf16 v[16:31], v[138:141], v[48:51], v[16:31]
	v_mfma_f32_32x32x16_bf16 v[0:15], v[154:157], v[48:51], v[0:15]
	v_add_f32_e32 v130, v130, v56
	v_add_f32_e32 v131, v131, v57
	v_add_f32_e32 v130, v130, v58
	v_add_f32_e32 v131, v131, v59
	v_add_f32_e32 v130, v130, v60
	v_add_f32_e32 v131, v131, v61
	v_add_f32_e32 v130, v130, v62
	v_add_f32_e32 v131, v131, v63
	v_cvt_pk_bf16_f32 v52, v56, v57
	v_cvt_pk_bf16_f32 v53, v58, v59
	v_cvt_pk_bf16_f32 v54, v60, v61
	v_cvt_pk_bf16_f32 v55, v62, v63
	v_fma_f32 v32, v32, s6, -v158
	v_fma_f32 v33, v33, s6, -v158
	v_fma_f32 v34, v34, s6, -v158
	v_fma_f32 v35, v35, s6, -v158
	v_fma_f32 v36, v36, s6, -v158
	v_fma_f32 v37, v37, s6, -v158
	v_fma_f32 v38, v38, s6, -v158
	v_fma_f32 v39, v39, s6, -v158
	v_exp_f32_e32 v32, v32
	v_exp_f32_e32 v33, v33
	v_exp_f32_e32 v34, v34
	v_exp_f32_e32 v35, v35
	v_exp_f32_e32 v36, v36
	v_exp_f32_e32 v37, v37
	v_exp_f32_e32 v38, v38
	v_exp_f32_e32 v39, v39
	v_mfma_f32_32x32x16_bf16 v[16:31], v[142:145], v[52:55], v[16:31]
	v_mfma_f32_32x32x16_bf16 v[0:15], v[118:121], v[52:55], v[0:15]
	v_add_f32_e32 v130, v130, v32
	v_add_f32_e32 v131, v131, v33
	v_add_f32_e32 v130, v130, v34
	v_add_f32_e32 v131, v131, v35
	v_add_f32_e32 v130, v130, v36
	v_add_f32_e32 v131, v131, v37
	v_add_f32_e32 v130, v130, v38
	v_add_f32_e32 v131, v131, v39
	v_cvt_pk_bf16_f32 v32, v32, v33
	v_cvt_pk_bf16_f32 v33, v34, v35
	v_cvt_pk_bf16_f32 v34, v36, v37
	v_cvt_pk_bf16_f32 v35, v38, v39
	v_fma_f32 v40, v40, s6, -v158
	v_fma_f32 v41, v41, s6, -v158
	v_fma_f32 v42, v42, s6, -v158
	v_fma_f32 v43, v43, s6, -v158
	v_fma_f32 v44, v44, s6, -v158
	v_fma_f32 v45, v45, s6, -v158
	v_fma_f32 v46, v46, s6, -v158
	v_fma_f32 v47, v47, s6, -v158
	v_exp_f32_e32 v40, v40
	v_exp_f32_e32 v41, v41
	v_exp_f32_e32 v42, v42
	v_exp_f32_e32 v43, v43
	v_exp_f32_e32 v44, v44
	v_exp_f32_e32 v45, v45
	v_exp_f32_e32 v46, v46
	v_exp_f32_e32 v47, v47
	v_mfma_f32_32x32x16_bf16 v[16:31], v[146:149], v[32:35], v[16:31]
	v_mfma_f32_32x32x16_bf16 v[0:15], v[122:125], v[32:35], v[0:15]
	v_add_f32_e32 v130, v130, v40
	v_add_f32_e32 v131, v131, v41
	v_add_f32_e32 v130, v130, v42
	v_add_f32_e32 v131, v131, v43
	v_add_f32_e32 v130, v130, v44
	v_add_f32_e32 v131, v131, v45
	v_add_f32_e32 v130, v130, v46
	v_add_f32_e32 v131, v131, v47
	v_cvt_pk_bf16_f32 v36, v40, v41
	v_cvt_pk_bf16_f32 v37, v42, v43
	v_cvt_pk_bf16_f32 v38, v44, v45
	v_cvt_pk_bf16_f32 v39, v46, v47
	v_add_f32_e32 v130, v130, v131
	v_add_f32_e32 v101, v101, v130
	v_mfma_f32_32x32x16_bf16 v[16:31], v[150:153], v[36:39], v[16:31]
	v_mfma_f32_32x32x16_bf16 v[0:15], v[126:129], v[36:39], v[0:15]
.Latt_done_a:
.LBB0_77:
	s_waitcnt vmcnt(1)
	ds_write_b128 v114, v[88:91] offset:9216
	s_waitcnt vmcnt(0)
	ds_write_b16 v115, v92 offset:27648
	ds_write_b16_d16_hi v115, v92 offset:27792
	ds_write_b16 v115, v93 offset:27936
	ds_write_b16_d16_hi v115, v93 offset:28080
	ds_write_b16 v115, v94 offset:28224
	ds_write_b16_d16_hi v115, v94 offset:28368
	ds_write_b16 v115, v95 offset:28512
	ds_write_b16_d16_hi v115, v95 offset:28656
	s_waitcnt lgkmcnt(0)
	s_barrier
	s_cmp_gt_u32 s28, s15
	s_cbranch_scc1 .LBB0_79
	global_load_dwordx4 v[88:91], v[106:107], off offset:-2048
	global_load_dwordx4 v[92:95], v[106:107], off
; #define LAS __attribute__((address_space(3)))
; __device__ __forceinline__ void attn_tile(const LAS unsigned char* Kb, const LAS unsigned char* Vb, const LAS f32x4* bp, const bf16x8 (&qr)[4], f32x16 (&o)[2], float& m, float& l, int r32, int hi) {
;     const float C2 = 0.125f * LOG2E;
;     f32x16 p0, p1;
; #pragma unroll
;     for (int j = 0; j < 4; ++j) { const f32x4 t0 = bp[j * 64], t1 = bp[(4 + j) * 64];
;         p0[4 * j] = t0[0]; p0[4 * j + 1] = t0[1]; p0[4 * j + 2] = t0[2]; p0[4 * j + 3] = t0[3]; p1[4 * j] = t1[0]; p1[4 * j + 1] = t1[1]; p1[4 * j + 2] = t1[2]; p1[4 * j + 3] = t1[3]; }
; #pragma unroll
;     for (int d0 = 0; d0 < 4; ++d0) {
;         const bf16x8 a0 = *(const LAS bf16x8*)(Kb + r32 * 144 + d0 * 32 + hi * 16);
;         const bf16x8 a1 = *(const LAS bf16x8*)(Kb + (32 + r32) * 144 + d0 * 32 + hi * 16);
;         p0 = __builtin_amdgcn_mfma_f32_32x32x16_bf16(a0, qr[d0], p0, 0, 0, 0);
;         p1 = __builtin_amdgcn_mfma_f32_32x32x16_bf16(a1, qr[d0], p1, 0, 0, 0);
;     }
;     float mx = fmaxf(p0[0], p1[0]);
; #pragma unroll
;     for (int r = 1; r < 16; ++r) mx = fmaxf(mx, fmaxf(p0[r], p1[r]));
;     mx = fmaxf(mx, __shfl_xor(mx, 32)) * C2;
;     if (__any(mx > m + 8.0f)) {
;         const float mn = fmaxf(m, mx), scl = __builtin_amdgcn_exp2f(m - mn); m = mn; l *= scl;
; #pragma unroll
;         for (int r = 0; r < 16; ++r) { o[0][r] *= scl; o[1][r] *= scl; }
;     }
;     float ls = 0.f; const float nm = -m;
; #pragma unroll
;     for (int r = 0; r < 16; ++r) { p0[r] = __builtin_amdgcn_exp2f(p0[r] * C2 + nm); p1[r] = __builtin_amdgcn_exp2f(p1[r] * C2 + nm); ls += p0[r] + p1[r]; }
; __device__ __forceinline__ void attn_prompt_unit(const Params& P, LAS unsigned char* lds, int li, int b, int h, int g4, const int tid) {
;     ...
;         if (kt + 1 >= cw - 8 && kt + 1 <= cw) attn_tile(lds + AT_KOFF + 9216, lds + AT_VOFF + 9216, btl + min(cw - kt - 1, 3) * 1024, qr, o, m, l, r32, hi);
.LBB0_79:
	s_add_i32 s29, s28, 1
	s_cmp_lt_i32 s29, s25
	s_cselect_b64 s[30:31], -1, 0
	s_cmp_ge_i32 s28, s23
	s_cselect_b64 s[28:29], -1, 0
	s_or_b64 s[28:29], s[28:29], s[30:31]
	s_and_b64 vcc, exec, s[28:29]
	s_cbranch_vccnz .LBB0_83
	s_add_i32 s28, s22, s26
	s_min_i32 s28, s28, 3
	s_cmp_eq_u32 s28, 3
	s_cbranch_scc1 .Latt_const_b
	v_lshl_add_u32 v158, s28, 14, v103
	ds_read_b128 v[48:51], v158 offset:36864
	ds_read_b128 v[52:55], v158 offset:37888
	ds_read_b128 v[56:59], v158 offset:38912
	ds_read_b128 v[60:63], v158 offset:39936
	ds_read_b128 v[138:141], v116 offset:9216
	ds_read_b128 v[142:145], v116 offset:13824
	ds_read_b128 v[32:35], v158 offset:40960
	ds_read_b128 v[36:39], v158 offset:41984
	ds_read_b128 v[40:43], v158 offset:43008
	ds_read_b128 v[44:47], v158 offset:44032
	ds_read_b128 v[146:149], v116 offset:9248
	ds_read_b128 v[150:153], v116 offset:13856
	ds_read_b128 v[154:157], v116 offset:9280
	ds_read_b128 v[118:121], v116 offset:13888
	ds_read_b128 v[122:125], v116 offset:9312
	v_add_u32_e32 v133, v113, v112
	v_xor_b32_e32 v132, 32, v200
	s_waitcnt lgkmcnt(10)
	v_mfma_f32_32x32x16_bf16 v[48:63], v[138:141], v[64:67], v[48:63]
	ds_read_b128 v[126:129], v116 offset:13920
	s_waitcnt lgkmcnt(6)
	v_mfma_f32_32x32x16_bf16 v[32:47], v[142:145], v[64:67], v[32:47]
	v_lshlrev_b32_e32 v132, 2, v132
	s_waitcnt lgkmcnt(5)
	v_mfma_f32_32x32x16_bf16 v[48:63], v[146:149], v[68:71], v[48:63]
	s_waitcnt lgkmcnt(4)
	v_mfma_f32_32x32x16_bf16 v[32:47], v[150:153], v[68:71], v[32:47]
	s_waitcnt lgkmcnt(3)
	v_mfma_f32_32x32x16_bf16 v[48:63], v[154:157], v[72:75], v[48:63]
	s_waitcnt lgkmcnt(2)
	v_mfma_f32_32x32x16_bf16 v[32:47], v[118:121], v[72:75], v[32:47]
	s_waitcnt lgkmcnt(1)
	v_mfma_f32_32x32x16_bf16 v[48:63], v[122:125], v[80:83], v[48:63]
	s_waitcnt lgkmcnt(0)
	v_mfma_f32_32x32x16_bf16 v[32:47], v[126:129], v[80:83], v[32:47]
	ds_read_b128 v[138:141], v133 offset:27648
	ds_read_b128 v[142:145], v133 offset:27680
	ds_read_b128 v[146:149], v133 offset:27712
	ds_read_b128 v[150:153], v133 offset:27744
	ds_read_b128 v[154:157], v133 offset:32256
	ds_read_b128 v[118:121], v133 offset:32288
	ds_read_b128 v[122:125], v133 offset:32320
	ds_read_b128 v[126:129], v133 offset:32352
	v_add_f32_e32 v159, 0x41000000, v117
	s_nop 1
	v_max3_f32 v130, v48, v49, v50
	v_max3_f32 v130, v130, v51, v52
	v_max3_f32 v130, v130, v53, v54
	v_max3_f32 v131, v32, v33, v34
	v_max3_f32 v130, v130, v55, v56
	v_max3_f32 v131, v131, v35, v36
	v_max3_f32 v130, v130, v57, v58
	v_max3_f32 v131, v131, v37, v38
	v_max3_f32 v130, v130, v59, v60
	v_max3_f32 v131, v131, v39, v40
	v_max3_f32 v130, v130, v61, v62
	v_max3_f32 v131, v131, v41, v42
	v_max_f32_e32 v130, v130, v63
	v_max3_f32 v131, v131, v43, v44
	v_max3_f32 v131, v131, v45, v46
	v_max_f32_e32 v131, v131, v47
	v_max_f32_e32 v130, v130, v131
	ds_bpermute_b32 v131, v132, v130
	s_waitcnt lgkmcnt(0)
	v_max_f32_e32 v130, v130, v131
	v_mul_f32_e32 v130, 0x3e38aa3b, v130
	v_cmp_gt_f32_e32 vcc, v130, v159
	s_cbranch_vccz .Latt_keep_b
	v_max_f32_e32 v131, v117, v130
	v_sub_f32_e32 v117, v117, v131
	v_exp_f32_e32 v130, v117
	v_mov_b32_e32 v117, v131
	v_mul_f32_e32 v101, v101, v130
	v_pk_mul_f32 v[0:1], v[0:1], v[130:131] op_sel_hi:[1,0]
	v_pk_mul_f32 v[2:3], v[2:3], v[130:131] op_sel_hi:[1,0]
	v_pk_mul_f32 v[4:5], v[4:5], v[130:131] op_sel_hi:[1,0]
	v_pk_mul_f32 v[6:7], v[6:7], v[130:131] op_sel_hi:[1,0]
	v_pk_mul_f32 v[8:9], v[8:9], v[130:131] op_sel_hi:[1,0]
	v_pk_mul_f32 v[10:11], v[10:11], v[130:131] op_sel_hi:[1,0]
	v_pk_mul_f32 v[12:13], v[12:13], v[130:131] op_sel_hi:[1,0]
	v_pk_mul_f32 v[14:15], v[14:15], v[130:131] op_sel_hi:[1,0]
	v_pk_mul_f32 v[16:17], v[16:17], v[130:131] op_sel_hi:[1,0]
	v_pk_mul_f32 v[18:19], v[18:19], v[130:131] op_sel_hi:[1,0]
	v_pk_mul_f32 v[20:21], v[20:21], v[130:131] op_sel_hi:[1,0]
	v_pk_mul_f32 v[22:23], v[22:23], v[130:131] op_sel_hi:[1,0]
	v_pk_mul_f32 v[24:25], v[24:25], v[130:131] op_sel_hi:[1,0]
	v_pk_mul_f32 v[26:27], v[26:27], v[130:131] op_sel_hi:[1,0]
	v_pk_mul_f32 v[28:29], v[28:29], v[130:131] op_sel_hi:[1,0]
	v_pk_mul_f32 v[30:31], v[30:31], v[130:131] op_sel_hi:[1,0]

; #define LAS __attribute__((address_space(3)))
; __device__ __forceinline__ void attn_tile(const LAS unsigned char* Kb, const LAS unsigned char* Vb, const LAS f32x4* bp, const bf16x8 (&qr)[4], f32x16 (&o)[2], float& m, float& l, int r32, int hi) {
;     const float C2 = 0.125f * LOG2E;
;     f32x16 p0, p1;
; #pragma unroll
;     for (int j = 0; j < 4; ++j) { const f32x4 t0 = bp[j * 64], t1 = bp[(4 + j) * 64];
;         p0[4 * j] = t0[0]; p0[4 * j + 1] = t0[1]; p0[4 * j + 2] = t0[2]; p0[4 * j + 3] = t0[3]; p1[4 * j] = t1[0]; p1[4 * j + 1] = t1[1]; p1[4 * j + 2] = t1[2]; p1[4 * j + 3] = t1[3]; }
; #pragma unroll
;     for (int d0 = 0; d0 < 4; ++d0) {
;         const bf16x8 a0 = *(const LAS bf16x8*)(Kb + r32 * 144 + d0 * 32 + hi * 16);
;         const bf16x8 a1 = *(const LAS bf16x8*)(Kb + (32 + r32) * 144 + d0 * 32 + hi * 16);
;         p0 = __builtin_amdgcn_mfma_f32_32x32x16_bf16(a0, qr[d0], p0, 0, 0, 0);
;         p1 = __builtin_amdgcn_mfma_f32_32x32x16_bf16(a1, qr[d0], p1, 0, 0, 0);
;     }
;     float mx = fmaxf(p0[0], p1[0]);
; #pragma unroll
;     for (int r = 1; r < 16; ++r) mx = fmaxf(mx, fmaxf(p0[r], p1[r]));
;     mx = fmaxf(mx, __shfl_xor(mx, 32)) * C2;
;     if (__any(mx > m + 8.0f)) {
;         const float mn = fmaxf(m, mx), scl = __builtin_amdgcn_exp2f(m - mn); m = mn; l *= scl;
; #pragma unroll
;         for (int r = 0; r < 16; ++r) { o[0][r] *= scl; o[1][r] *= scl; }
;     }
; __device__ __forceinline__ void attn_prompt_unit(const Params& P, LAS unsigned char* lds, int li, int b, int h, int g4, const int tid) {
;     ...
;         if (kt + 1 >= cw - 8 && kt + 1 <= cw) attn_tile(lds + AT_KOFF + 9216, lds + AT_VOFF + 9216, btl + min(cw - kt - 1, 3) * 1024, qr, o, m, l, r32, hi);
.Latt_const_b:
	v_add_u32_e32 v158, 0xc000, v103
	ds_read_b32 v158, v158 offset:36864
	ds_read_b128 v[138:141], v116 offset:9216
	ds_read_b128 v[142:145], v116 offset:13824
	ds_read_b128 v[146:149], v116 offset:9248
	ds_read_b128 v[150:153], v116 offset:13856
	ds_read_b128 v[154:157], v116 offset:9280
	ds_read_b128 v[118:121], v116 offset:13888
	ds_read_b128 v[122:125], v116 offset:9312
	ds_read_b128 v[126:129], v116 offset:13920
	v_add_u32_e32 v133, v113, v112
	v_xor_b32_e32 v132, 32, v200
	s_waitcnt lgkmcnt(7)
	v_mfma_f32_32x32x16_bf16 v[48:63], v[138:141], v[64:67], 0
	s_waitcnt lgkmcnt(6)
	v_mfma_f32_32x32x16_bf16 v[32:47], v[142:145], v[64:67], 0
	v_lshlrev_b32_e32 v132, 2, v132
	s_waitcnt lgkmcnt(5)
	v_mfma_f32_32x32x16_bf16 v[48:63], v[146:149], v[68:71], v[48:63]
	s_waitcnt lgkmcnt(4)
	v_mfma_f32_32x32x16_bf16 v[32:47], v[150:153], v[68:71], v[32:47]
	s_waitcnt lgkmcnt(3)
	v_mfma_f32_32x32x16_bf16 v[48:63], v[154:157], v[72:75], v[48:63]
	s_waitcnt lgkmcnt(2)
	v_mfma_f32_32x32x16_bf16 v[32:47], v[118:121], v[72:75], v[32:47]
	s_waitcnt lgkmcnt(1)
	v_mfma_f32_32x32x16_bf16 v[48:63], v[122:125], v[80:83], v[48:63]
	s_waitcnt lgkmcnt(0)
	v_mfma_f32_32x32x16_bf16 v[32:47], v[126:129], v[80:83], v[32:47]
	ds_read_b128 v[138:141], v133 offset:27648
	ds_read_b128 v[142:145], v133 offset:27680
	ds_read_b128 v[146:149], v133 offset:27712
	ds_read_b128 v[150:153], v133 offset:27744
	ds_read_b128 v[154:157], v133 offset:32256
	ds_read_b128 v[118:121], v133 offset:32288
	ds_read_b128 v[122:125], v133 offset:32320
	ds_read_b128 v[126:129], v133 offset:32352
	v_add_f32_e32 v159, 0x41000000, v117
	s_nop 1
	v_max3_f32 v130, v48, v49, v50
	v_max3_f32 v130, v130, v51, v52
	v_max3_f32 v130, v130, v53, v54
	v_max3_f32 v131, v32, v33, v34
	v_max3_f32 v130, v130, v55, v56
	v_max3_f32 v131, v131, v35, v36
	v_max3_f32 v130, v130, v57, v58
	v_max3_f32 v131, v131, v37, v38
	v_max3_f32 v130, v130, v59, v60
	v_max3_f32 v131, v131, v39, v40
	v_max3_f32 v130, v130, v61, v62
	v_max3_f32 v131, v131, v41, v42
	v_max_f32_e32 v130, v130, v63
	v_max3_f32 v131, v131, v43, v44
	v_max3_f32 v131, v131, v45, v46
	v_max_f32_e32 v131, v131, v47
	v_max_f32_e32 v130, v130, v131
	ds_bpermute_b32 v131, v132, v130
	s_waitcnt lgkmcnt(0)
	v_max_f32_e32 v130, v130, v131
	v_add_f32_e32 v130, v130, v158
	v_mul_f32_e32 v130, 0x3e38aa3b, v130
	v_cmp_gt_f32_e32 vcc, v130, v159
	s_cbranch_vccz .Latt_keep_bc
	v_max_f32_e32 v131, v117, v130
	v_sub_f32_e32 v117, v117, v131
	v_exp_f32_e32 v130, v117
	v_mov_b32_e32 v117, v131
	v_mul_f32_e32 v101, v101, v130
	v_pk_mul_f32 v[0:1], v[0:1], v[130:131] op_sel_hi:[1,0]
	v_pk_mul_f32 v[2:3], v[2:3], v[130:131] op_sel_hi:[1,0]
	v_pk_mul_f32 v[4:5], v[4:5], v[130:131] op_sel_hi:[1,0]
	v_pk_mul_f32 v[6:7], v[6:7], v[130:131] op_sel_hi:[1,0]
	v_pk_mul_f32 v[8:9], v[8:9], v[130:131] op_sel_hi:[1,0]
	v_pk_mul_f32 v[10:11], v[10:11], v[130:131] op_sel_hi:[1,0]
	v_pk_mul_f32 v[12:13], v[12:13], v[130:131] op_sel_hi:[1,0]
	v_pk_mul_f32 v[14:15], v[14:15], v[130:131] op_sel_hi:[1,0]
	v_pk_mul_f32 v[16:17], v[16:17], v[130:131] op_sel_hi:[1,0]
	v_pk_mul_f32 v[18:19], v[18:19], v[130:131] op_sel_hi:[1,0]
	v_pk_mul_f32 v[20:21], v[20:21], v[130:131] op_sel_hi:[1,0]
	v_pk_mul_f32 v[22:23], v[22:23], v[130:131] op_sel_hi:[1,0]
	v_pk_mul_f32 v[24:25], v[24:25], v[130:131] op_sel_hi:[1,0]
	v_pk_mul_f32 v[26:27], v[26:27], v[130:131] op_sel_hi:[1,0]
	v_pk_mul_f32 v[28:29], v[28:29], v[130:131] op_sel_hi:[1,0]
	v_pk_mul_f32 v[30:31], v[30:31], v[130:131] op_sel_hi:[1,0]

; #define AT_STORE(K_, V_, buf) do { *(LAS bf16x8*)(lds + AT_KOFF + (buf) * 9216 + srow * 144 + sch * 16) = K_; \
;         _Pragma("unroll") for (int j_ = 0; j_ < 8; ++j_) *(LAS short*)(lds + AT_VOFF + (buf) * 9216 + (8 * sch + j_) * 144 + vp * 2) = V_[j_]; } while (0)
; __device__ __forceinline__ void attn_prompt_unit(const Params& P, LAS unsigned char* lds, int li, int b, int h, int g4, const int tid) {
;     ...
;         if (kt + 2 <= kt_hi) AT_STORE(kA, vA, 0);
.Latt_done_b:
.LBB0_83:
	s_andn2_b64 vcc, exec, s[18:19]
	s_cbranch_vccnz .LBB0_85
	ds_write_b128 v114, v[76:79]
	ds_write_b16 v115, v84 offset:18432
	ds_write_b16_d16_hi v115, v84 offset:18576
	ds_write_b16 v115, v85 offset:18720
	ds_write_b16_d16_hi v115, v85 offset:18864
	ds_write_b16 v115, v86 offset:19008
	ds_write_b16_d16_hi v115, v86 offset:19152
	ds_write_b16 v115, v87 offset:19296
	ds_write_b16_d16_hi v115, v87 offset:19440
